# prep_rows software pipelined: next row's four x4 loads issued before the current row's sum-of-squares reduction (double buffer v52-v67)
# speedup vs baseline: 1.0466x; 1.0045x over previous
; DI int tid_opaque() { int t = threadIdx.x; asm volatile("" : "+v"(t)); return t; }
; DI void prep_rows(const Params& p) {
;   const int tt_ = tid_opaque();
;   const int l = tt_ & 63, gw = blockIdx.x * 8 + (tt_ >> 6), nw = gridDim.x * 8;
;   for (int row = gw; row < T_TOK; row += nw) {
;     const float* src = row < TP ? p.x_prompt + (long)row * 1024 : p.x_sample + (long)(row - TP) * 1024;
;     float4 v[4];
;     float s = 0.f;
; #pragma unroll
;     for (int i = 0; i < 4; ++i) {
;       v[i] = ((const float4*)src)[l + 64 * i];
.Lprio_done:
	v_and_b32_e32 v182, 0x3ff, v0
	s_add_u32 s96, s0, 0x8a8
	v_mov_b32_e32 v1, v182
	s_addc_u32 s97, s1, 0
	s_lshl_b32 s92, s2, 3
	v_ashrrev_i32_e32 v2, 6, v1
	v_add_u32_e32 v2, s92, v2
	s_mov_b32 s3, 0x14000
	s_mov_b32 s82, s2
	s_waitcnt lgkmcnt(0)
	s_lshl_b32 s34, s42, 3
	v_cmp_gt_i32_e32 vcc, s3, v2
	v_mbcnt_lo_u32_b32 v183, -1, 0
	s_and_saveexec_b64 s[8:9], vcc
	s_cbranch_execz .LBB0_7
	v_mbcnt_hi_u32_b32 v3, -1, v183
	v_and_b32_e32 v10, 63, v1
	v_and_b32_e32 v1, 64, v3
	v_add_u32_e32 v4, 64, v1
	v_xor_b32_e32 v1, 1, v3
	v_cmp_lt_i32_e64 s[4:5], v1, v4
	v_xor_b32_e32 v6, 2, v3
	s_load_dwordx2 s[10:11], s[0:1], 0x60
	v_cndmask_b32_e64 v1, v3, v1, s[4:5]
	v_cmp_lt_i32_e64 s[4:5], v6, v4
	v_mov_b32_e32 v5, 0
	s_ashr_i32 s35, s34, 31
	v_cndmask_b32_e64 v6, v3, v6, s[4:5]
	v_lshlrev_b32_e32 v16, 2, v6
	v_xor_b32_e32 v6, 4, v3
	v_cmp_lt_i32_e64 s[4:5], v6, v4
	v_cmp_eq_u32_e32 vcc, 0, v10
	v_lshlrev_b32_e32 v1, 2, v1
	v_cndmask_b32_e64 v6, v3, v6, s[4:5]
	v_lshlrev_b32_e32 v17, 2, v6
	v_xor_b32_e32 v6, 8, v3
	v_cmp_lt_i32_e64 s[4:5], v6, v4
	s_lshl_b64 s[12:13], s[34:35], 12
	s_mov_b64 s[14:15], 0
	v_cndmask_b32_e64 v6, v3, v6, s[4:5]
	v_lshlrev_b32_e32 v18, 2, v6
	v_xor_b32_e32 v6, 16, v3
	v_cmp_lt_i32_e64 s[4:5], v6, v4
	s_movk_i32 s3, 0x3fff
	v_mov_b32_e32 v11, v5
	v_cndmask_b32_e64 v6, v3, v6, s[4:5]
	v_lshlrev_b32_e32 v19, 2, v6
	v_xor_b32_e32 v6, 32, v3
	v_cmp_lt_i32_e64 s[4:5], v6, v4
	v_lshlrev_b32_e32 v4, 3, v10
	v_lshlrev_b32_e32 v10, 4, v10
	v_cndmask_b32_e64 v3, v3, v6, s[4:5]
	s_load_dwordx4 s[4:7], s[0:1], 0x0
	s_waitcnt lgkmcnt(0)
	v_lshl_add_u64 v[6:7], s[10:11], 0, v[4:5]
	s_load_dwordx2 s[10:11], s[0:1], 0xf8
	v_lshlrev_b32_e32 v20, 2, v3
	v_ashrrev_i32_e32 v3, 31, v2
	v_lshlrev_b64 v[8:9], 12, v[2:3]
	v_lshl_add_u64 v[8:9], s[4:5], 0, v[8:9]
	s_mov_b32 s18, 0x13fff
	v_add_u32_e32 v72, 0xffffc000, v2
	v_mov_b32_e32 v73, 0
	v_cmp_lt_i32_e64 s[4:5], s3, v2
	v_lshlrev_b64 v[72:73], 12, v[72:73]
	s_waitcnt lgkmcnt(0)
	v_lshl_add_u64 v[72:73], s[6:7], 0, v[72:73]
	v_cndmask_b32_e64 v70, v8, v72, s[4:5]
	v_cndmask_b32_e64 v71, v9, v73, s[4:5]
	v_lshl_add_u64 v[70:71], v[70:71], 0, v[10:11]
	global_load_dwordx4 v[52:55], v[70:71], off
	global_load_dwordx4 v[56:59], v[70:71], off offset:1024
	global_load_dwordx4 v[60:63], v[70:71], off offset:2048
	global_load_dwordx4 v[64:67], v[70:71], off offset:3072
	s_waitcnt vmcnt(0)
	s_branch .LBB0_3

; DI u32x2 pack4(float a, float b, float c, float d) { u32x2 r; r.x = pack2(a, b); r.y = pack2(c, d); return r; }
; DI void prep_rows(const Params& p) {
;     ...
;   for (int row = gw; row < T_TOK; row += nw) {
;     const float* src = row < TP ? p.x_prompt + (long)row * 1024 : p.x_sample + (long)(row - TP) * 1024;
;     float4 v[4];
;     float s = 0.f;
; #pragma unroll
;     for (int i = 0; i < 4; ++i) {
;       v[i] = ((const float4*)src)[l + 64 * i];
;       s += v[i].x * v[i].x + v[i].y * v[i].y + v[i].z * v[i].z + v[i].w * v[i].w;
;     }
; #pragma unroll
;     for (int o = 1; o < 64; o <<= 1) s += __shfl_xor(s, o);
; #pragma unroll
;     for (int i = 0; i < 4; ++i) {
;       *(u32x2*)(p.buf0 + (long)row * 1024 + (l + 64 * i) * 4) = pack4(v[i].x, v[i].y, v[i].z, v[i].w);
;     }
;     if (l == 0) p.ssq[row] = s;
;   }
.LBB0_3:
	v_mov_b64_e32 v[12:13], v[2:3]
	v_lshl_add_u64 v[68:69], v[2:3], 0, s[34:35]
	v_lshl_add_u64 v[70:71], v[8:9], 0, s[12:13]
	v_mov_b32_e32 v73, 0
	v_add_u32_e32 v72, 0xffffc000, v68
	v_cmp_lt_i32_e64 s[4:5], s3, v68
	v_lshlrev_b64 v[72:73], 12, v[72:73]
	v_cmp_ge_i32_e64 s[16:17], s18, v68
	v_lshl_add_u64 v[72:73], s[6:7], 0, v[72:73]
	s_waitcnt vmcnt(4) lgkmcnt(0)
	v_mov_b64_e32 v[22:23], v[52:53]
	v_mov_b64_e32 v[24:25], v[54:55]
	v_mov_b64_e32 v[26:27], v[56:57]
	v_mov_b64_e32 v[28:29], v[58:59]
	v_mov_b64_e32 v[30:31], v[60:61]
	v_mov_b64_e32 v[32:33], v[62:63]
	v_mov_b64_e32 v[34:35], v[64:65]
	v_mov_b64_e32 v[36:37], v[66:67]
	v_cndmask_b32_e64 v70, v70, v72, s[4:5]
	v_cndmask_b32_e64 v71, v71, v73, s[4:5]
	v_lshl_add_u64 v[70:71], v[70:71], 0, v[10:11]
	s_and_saveexec_b64 s[4:5], s[16:17]
	global_load_dwordx4 v[52:55], v[70:71], off
	global_load_dwordx4 v[56:59], v[70:71], off offset:1024
	global_load_dwordx4 v[60:63], v[70:71], off offset:2048
	global_load_dwordx4 v[64:67], v[70:71], off offset:3072
	s_or_b64 exec, exec, s[4:5]
	v_pk_mul_f32 v[14:15], v[22:23], v[22:23]
	v_pk_mul_f32 v[40:41], v[26:27], v[26:27]
	v_pk_mul_f32 v[38:39], v[24:25], v[24:25]
	v_pk_mul_f32 v[42:43], v[28:29], v[28:29]
	v_pk_mul_f32 v[44:45], v[30:31], v[30:31]
	v_add_f32_e32 v4, v40, v41
	v_add_f32_e32 v14, v14, v15
	v_pk_mul_f32 v[46:47], v[32:33], v[32:33]
	v_pk_mul_f32 v[48:49], v[34:35], v[34:35]
	v_add_f32_e32 v15, v44, v45
	v_add_f32_e32 v4, v4, v42
	v_add_f32_e32 v14, v14, v38
	v_pk_mul_f32 v[50:51], v[36:37], v[36:37]
	v_add_f32_e32 v21, v48, v49
	v_add_f32_e32 v15, v15, v46
	v_add_f32_e32 v4, v4, v43
	v_add_f32_e32 v14, v14, v39
	v_add_f32_e32 v21, v21, v50
	v_add_f32_e32 v15, v15, v47
	v_add_f32_e32 v4, v14, v4
	v_add_f32_e32 v21, v21, v51
	v_add_f32_e32 v4, v4, v15
	v_add_f32_e32 v4, v4, v21
	ds_bpermute_b32 v14, v1, v4
	s_waitcnt lgkmcnt(0)
	v_add_f32_e32 v4, v4, v14
	ds_bpermute_b32 v14, v16, v4
	s_waitcnt lgkmcnt(0)
	v_add_f32_e32 v4, v4, v14
	ds_bpermute_b32 v21, v17, v4
	v_lshlrev_b64 v[14:15], 11, v[12:13]
	v_lshl_add_u64 v[38:39], v[6:7], 0, v[14:15]
	v_cvt_pk_bf16_f32 v14, v22, v23
	v_cvt_pk_bf16_f32 v15, v24, v25
	s_waitcnt lgkmcnt(0)
	v_add_f32_e32 v4, v4, v21
	ds_bpermute_b32 v21, v18, v4
	v_cvt_pk_bf16_f32 v22, v26, v27
	v_cvt_pk_bf16_f32 v23, v28, v29
	global_store_dwordx2 v[38:39], v[14:15], off
	global_store_dwordx2 v[38:39], v[22:23], off offset:512
	v_cvt_pk_bf16_f32 v24, v30, v31
	s_waitcnt lgkmcnt(0)
	v_add_f32_e32 v4, v4, v21
	ds_bpermute_b32 v21, v19, v4
	v_cvt_pk_bf16_f32 v25, v32, v33
	v_cvt_pk_bf16_f32 v22, v34, v35
	v_cvt_pk_bf16_f32 v23, v36, v37
	global_store_dwordx2 v[38:39], v[24:25], off offset:1024
	s_waitcnt lgkmcnt(0)
	v_add_f32_e32 v4, v4, v21
	ds_bpermute_b32 v14, v20, v4
	global_store_dwordx2 v[38:39], v[22:23], off offset:1536
	s_and_saveexec_b64 s[4:5], vcc
	s_cbranch_execz .LBB0_2
	s_waitcnt lgkmcnt(0)
	v_add_f32_e32 v4, v4, v14
	v_lshl_add_u64 v[12:13], v[12:13], 2, s[10:11]
	global_store_dword v[12:13], v4, off
	s_branch .LBB0_2
